# plus: branch-free rescale decision and v_mov_b64 splat in the sliding-window loop
# baseline (speedup 1.0000x reference)
.LBB0_1540:
	s_add_i32 s0, s76, s0
	s_cmp_eq_u32 s0, -1
	s_cselect_b64 vcc, -1, 0
	s_cmp_eq_u32 s0, -9
	v_cndmask_b32_e32 v33, 63, v201, vcc
	s_cselect_b64 vcc, -1, 0
	v_cndmask_b32_e32 v94, 0, v202, vcc
	v_cmp_ge_i32_e32 vcc, v33, v94
	v_cmp_lt_i32_e64 s[0:1], -1, v33
	s_and_b64 vcc, vcc, s[0:1]
	s_cbranch_vccz .LBB0_1557
	v_lshl_add_u32 v101, v98, 13, v153
	ds_read_b128 v[102:105], v101
	ds_read_b128 v[106:109], v101 offset:512
	v_cndmask_b32_e64 v34, v227, -v32, vcc
	v_mov_b32_e32 v35, v34
	v_mov_b64_e32 v[36:37], v[34:35]
	v_mov_b64_e32 v[38:39], v[34:35]
	v_mov_b64_e32 v[40:41], v[34:35]
	v_mov_b64_e32 v[42:43], v[34:35]
	v_mov_b64_e32 v[44:45], v[34:35]
	v_mov_b64_e32 v[46:47], v[34:35]
	v_mov_b64_e32 v[48:49], v[34:35]
	v_cmp_lt_i32_e64 s[0:1], 0, v94
	v_cmp_gt_i32_e64 s[2:3], 63, v33
	s_waitcnt lgkmcnt(1)
	v_mfma_f32_32x32x16_bf16 v[50:65], v[102:105], v[66:69], v[34:49]
	s_or_b64 s[0:1], s[0:1], s[2:3]
	s_and_b64 s[0:1], vcc, s[0:1]
	s_waitcnt lgkmcnt(0)
	v_mfma_f32_32x32x16_bf16 v[34:49], v[106:109], v[66:69], v[34:49]
	ds_read_b128 v[102:105], v101 offset:2048
	ds_read_b128 v[106:109], v101 offset:2560
	s_waitcnt lgkmcnt(1)
	v_mfma_f32_32x32x16_bf16 v[50:65], v[102:105], v[70:73], v[50:65]
	s_waitcnt lgkmcnt(0)
	v_mfma_f32_32x32x16_bf16 v[34:49], v[106:109], v[70:73], v[34:49]
	ds_read_b128 v[102:105], v101 offset:4096
	ds_read_b128 v[106:109], v101 offset:4608
	s_waitcnt lgkmcnt(1)
	v_mfma_f32_32x32x16_bf16 v[50:65], v[102:105], v[74:77], v[50:65]
	s_waitcnt lgkmcnt(0)
	v_mfma_f32_32x32x16_bf16 v[34:49], v[106:109], v[74:77], v[34:49]
	ds_read_b128 v[102:105], v101 offset:6144
	ds_read_b128 v[106:109], v101 offset:6656
	v_cndmask_b32_e64 v101, 0, 1, s[0:1]
	v_cmp_ne_u32_e32 vcc, 0, v101
	s_waitcnt lgkmcnt(1)
	v_mfma_f32_32x32x16_bf16 v[50:65], v[102:105], v[78:81], v[50:65]
	s_waitcnt lgkmcnt(0)
	v_mfma_f32_32x32x16_bf16 v[34:49], v[106:109], v[78:81], v[34:49]
	s_cbranch_vccz .LBB0_1545
	v_cmp_lt_i32_e64 s[2:3], v154, v94
	v_cmp_gt_i32_e64 s[4:5], v154, v33
	v_cmp_lt_i32_e64 s[14:15], v155, v94
	v_cmp_gt_i32_e64 s[16:17], v155, v33
	v_cmp_lt_i32_e64 s[18:19], v157, v94
	v_cmp_gt_i32_e64 s[20:21], v157, v33
	v_cmp_lt_i32_e64 s[22:23], v159, v94
	v_cmp_gt_i32_e64 s[24:25], v159, v33
	v_cmp_lt_i32_e64 s[26:27], v161, v94
	v_cmp_gt_i32_e64 s[28:29], v161, v33
	v_cmp_lt_i32_e64 s[30:31], v163, v94
	v_cmp_gt_i32_e64 s[34:35], v163, v33
	v_cmp_lt_i32_e64 s[36:37], v165, v94
	v_cmp_gt_i32_e64 s[38:39], v165, v33
	v_cmp_lt_i32_e64 s[40:41], v167, v94
	v_cmp_gt_i32_e64 s[42:43], v167, v33
	v_cmp_lt_i32_e64 s[44:45], v185, v94
	v_cmp_gt_i32_e64 s[46:47], v185, v33
	v_cmp_lt_i32_e64 s[48:49], v187, v94
	v_cmp_gt_i32_e64 s[50:51], v187, v33
	v_cmp_lt_i32_e64 s[52:53], v189, v94
	v_cmp_gt_i32_e64 s[54:55], v189, v33
	v_cmp_lt_i32_e64 s[56:57], v191, v94
	v_cmp_gt_i32_e64 s[58:59], v191, v33
	v_cmp_lt_i32_e64 s[60:61], v193, v94
	v_cmp_gt_i32_e64 s[62:63], v193, v33
	v_cmp_lt_i32_e64 s[64:65], v195, v94
	v_cmp_gt_i32_e64 s[66:67], v195, v33
	v_cmp_lt_i32_e64 s[68:69], v197, v94
	v_cmp_gt_i32_e64 s[70:71], v197, v33
	s_or_b64 s[2:3], s[2:3], s[4:5]
	s_or_b64 s[14:15], s[14:15], s[16:17]
	s_or_b64 s[18:19], s[18:19], s[20:21]
	s_or_b64 s[22:23], s[22:23], s[24:25]
	s_or_b64 s[26:27], s[26:27], s[28:29]
	s_or_b64 s[30:31], s[30:31], s[34:35]
	s_or_b64 s[36:37], s[36:37], s[38:39]
	s_or_b64 s[40:41], s[40:41], s[42:43]
	s_or_b64 s[44:45], s[44:45], s[46:47]
	s_or_b64 s[48:49], s[48:49], s[50:51]
	s_or_b64 s[52:53], s[52:53], s[54:55]
	s_or_b64 s[56:57], s[56:57], s[58:59]
	s_or_b64 s[60:61], s[60:61], s[62:63]
	s_or_b64 s[64:65], s[64:65], s[66:67]
	s_or_b64 s[68:69], s[68:69], s[70:71]
	v_cmp_lt_i32_e64 s[72:73], v199, v94
	v_cmp_gt_i32_e64 s[74:75], v199, v33
	v_cmp_lt_i32_e32 vcc, v114, v94
	v_cmp_gt_i32_e64 s[0:1], v114, v33
	v_cndmask_b32_e64 v34, v34, v227, s[2:3]
	v_cmp_lt_i32_e64 s[2:3], v203, v94
	v_cmp_ge_i32_e64 s[4:5], v114, v33
	v_cndmask_b32_e64 v35, v35, v227, s[14:15]
	v_cmp_lt_i32_e64 s[14:15], v156, v94
	v_cmp_gt_i32_e64 s[16:17], v156, v33
	v_cndmask_b32_e64 v36, v36, v227, s[18:19]
	v_cmp_lt_i32_e64 s[18:19], v158, v94
	v_cmp_gt_i32_e64 s[20:21], v158, v33
	v_cndmask_b32_e64 v37, v37, v227, s[22:23]
	v_cmp_lt_i32_e64 s[22:23], v160, v94
	v_cmp_gt_i32_e64 s[24:25], v160, v33
	v_cndmask_b32_e64 v38, v38, v227, s[26:27]
	v_cmp_lt_i32_e64 s[26:27], v162, v94
	v_cmp_gt_i32_e64 s[28:29], v162, v33
	v_cndmask_b32_e64 v39, v39, v227, s[30:31]
	v_cmp_lt_i32_e64 s[30:31], v164, v94
	v_cmp_gt_i32_e64 s[34:35], v164, v33
	v_cndmask_b32_e64 v40, v40, v227, s[36:37]
	v_cmp_lt_i32_e64 s[36:37], v166, v94
	v_cmp_gt_i32_e64 s[38:39], v166, v33
	v_cndmask_b32_e64 v41, v41, v227, s[40:41]
	v_cmp_lt_i32_e64 s[40:41], v184, v94
	v_cmp_gt_i32_e64 s[42:43], v184, v33
	v_cndmask_b32_e64 v42, v42, v227, s[44:45]
	v_cmp_lt_i32_e64 s[44:45], v186, v94
	v_cmp_gt_i32_e64 s[46:47], v186, v33
	v_cndmask_b32_e64 v43, v43, v227, s[48:49]
	v_cmp_lt_i32_e64 s[48:49], v188, v94
	v_cmp_gt_i32_e64 s[50:51], v188, v33
	v_cndmask_b32_e64 v44, v44, v227, s[52:53]
	v_cmp_lt_i32_e64 s[52:53], v190, v94
	v_cmp_gt_i32_e64 s[54:55], v190, v33
	v_cndmask_b32_e64 v45, v45, v227, s[56:57]
	v_cmp_lt_i32_e64 s[56:57], v192, v94
	v_cmp_gt_i32_e64 s[58:59], v192, v33
	v_cndmask_b32_e64 v46, v46, v227, s[60:61]
	v_cmp_lt_i32_e64 s[60:61], v194, v94
	v_cmp_gt_i32_e64 s[62:63], v194, v33
	v_cndmask_b32_e64 v47, v47, v227, s[64:65]
	v_cmp_lt_i32_e64 s[64:65], v196, v94
	v_cmp_gt_i32_e64 s[66:67], v196, v33
	v_cndmask_b32_e64 v48, v48, v227, s[68:69]
	v_cmp_lt_i32_e64 s[68:69], v198, v94
	v_cmp_gt_i32_e64 s[70:71], v198, v33
	s_or_b64 s[74:75], s[72:73], s[74:75]
	s_and_saveexec_b64 s[72:73], s[74:75]
	v_mov_b32_e32 v49, s33
	s_or_b64 exec, exec, s[72:73]
	s_or_b64 vcc, vcc, s[0:1]
	v_cndmask_b32_e32 v50, v50, v227, vcc
	s_or_b64 vcc, s[2:3], s[4:5]
	v_cndmask_b32_e32 v51, v51, v227, vcc
	s_or_b64 vcc, s[14:15], s[16:17]
	v_cndmask_b32_e32 v52, v52, v227, vcc
	s_or_b64 vcc, s[18:19], s[20:21]
	v_cndmask_b32_e32 v53, v53, v227, vcc
	s_or_b64 vcc, s[22:23], s[24:25]
	v_cndmask_b32_e32 v54, v54, v227, vcc
	s_or_b64 vcc, s[26:27], s[28:29]
	v_cndmask_b32_e32 v55, v55, v227, vcc
	s_or_b64 vcc, s[30:31], s[34:35]
	v_cndmask_b32_e32 v56, v56, v227, vcc
	s_or_b64 vcc, s[36:37], s[38:39]
	v_cndmask_b32_e32 v57, v57, v227, vcc
	s_or_b64 vcc, s[40:41], s[42:43]
	v_cndmask_b32_e32 v58, v58, v227, vcc
	s_or_b64 vcc, s[44:45], s[46:47]
	v_cndmask_b32_e32 v59, v59, v227, vcc
	s_or_b64 vcc, s[48:49], s[50:51]
	v_cndmask_b32_e32 v60, v60, v227, vcc
	s_or_b64 vcc, s[52:53], s[54:55]
	v_cndmask_b32_e32 v61, v61, v227, vcc
	s_or_b64 vcc, s[56:57], s[58:59]
	v_cndmask_b32_e32 v62, v62, v227, vcc
	s_or_b64 vcc, s[60:61], s[62:63]
	v_cndmask_b32_e32 v63, v63, v227, vcc
	s_or_b64 vcc, s[64:65], s[66:67]
	v_cndmask_b32_e32 v64, v64, v227, vcc
	s_or_b64 vcc, s[68:69], s[70:71]
	v_cndmask_b32_e32 v65, v65, v227, vcc
.LBB0_1545:
	s_nop 10
	v_max_f32_e32 v33, v34, v34
	v_max_f32_e32 v94, v50, v50
	v_max_f32_e32 v33, v94, v33
	v_max3_f32 v94, v35, v52, v36
	v_max3_f32 v33, v33, v51, v53
	v_max3_f32 v94, v94, v54, v38
	v_max3_f32 v33, v33, v37, v55
	v_max3_f32 v94, v94, v56, v40
	v_max3_f32 v33, v33, v39, v57
	v_max3_f32 v94, v94, v58, v42
	v_max3_f32 v33, v33, v41, v59
	v_max3_f32 v94, v94, v60, v44
	v_max3_f32 v33, v33, v43, v61
	v_max3_f32 v94, v94, v62, v46
	v_max3_f32 v33, v33, v45, v63
	v_max3_f32 v94, v94, v64, v48
	v_max3_f32 v33, v33, v47, v65
	v_max3_f32 v33, v33, v49, v94
	v_mov_b32_e32 v94, v33
	s_nop 1
	v_permlane32_swap_b32_e32 v33, v94
	v_max_f32_e32 v94, v94, v94
	v_max_f32_e32 v33, v33, v33
	v_max_f32_e32 v33, v33, v94
	s_mov_b32 s14, 0x41000000
	v_cmp_lg_f32_e64 s[2:3], s33, v33
	v_cmp_eq_u32_e64 s[0:1], 0, v100
	v_cmp_lt_f32_e64 s[4:5], s14, v33
	s_and_b64 s[0:1], s[0:1], s[2:3]
	s_and_b64 s[4:5], s[4:5], s[2:3]
	s_or_b64 s[4:5], s[4:5], s[0:1]
	v_cndmask_b32_e64 v94, 0, v33, s[4:5]
	v_cndmask_b32_e64 v100, v100, 1, s[2:3]
	v_cmp_neq_f32_e32 vcc, 0, v94
	s_cbranch_vccz .LBB0_1553
	v_exp_f32_e64 v33, -v94
	v_pk_add_f32 v[50:51], v[50:51], v[94:95] op_sel_hi:[1,0] neg_lo:[0,1] neg_hi:[0,1]
	v_pk_add_f32 v[34:35], v[34:35], v[94:95] op_sel_hi:[1,0] neg_lo:[0,1] neg_hi:[0,1]
	v_add_f32_e32 v32, v32, v94
	v_cndmask_b32_e64 v102, v33, 1.0, s[0:1]
	v_mul_f32_e32 v95, v95, v102
	v_pk_add_f32 v[52:53], v[52:53], v[94:95] op_sel_hi:[1,0] neg_lo:[0,1] neg_hi:[0,1]
	v_pk_add_f32 v[36:37], v[36:37], v[94:95] op_sel_hi:[1,0] neg_lo:[0,1] neg_hi:[0,1]
	v_pk_add_f32 v[54:55], v[54:55], v[94:95] op_sel_hi:[1,0] neg_lo:[0,1] neg_hi:[0,1]
	v_pk_add_f32 v[38:39], v[38:39], v[94:95] op_sel_hi:[1,0] neg_lo:[0,1] neg_hi:[0,1]
	v_pk_add_f32 v[56:57], v[56:57], v[94:95] op_sel_hi:[1,0] neg_lo:[0,1] neg_hi:[0,1]
	v_pk_add_f32 v[40:41], v[40:41], v[94:95] op_sel_hi:[1,0] neg_lo:[0,1] neg_hi:[0,1]
	v_pk_add_f32 v[58:59], v[58:59], v[94:95] op_sel_hi:[1,0] neg_lo:[0,1] neg_hi:[0,1]
	v_pk_add_f32 v[42:43], v[42:43], v[94:95] op_sel_hi:[1,0] neg_lo:[0,1] neg_hi:[0,1]
	v_pk_add_f32 v[60:61], v[60:61], v[94:95] op_sel_hi:[1,0] neg_lo:[0,1] neg_hi:[0,1]
	v_pk_add_f32 v[44:45], v[44:45], v[94:95] op_sel_hi:[1,0] neg_lo:[0,1] neg_hi:[0,1]
	v_pk_add_f32 v[62:63], v[62:63], v[94:95] op_sel_hi:[1,0] neg_lo:[0,1] neg_hi:[0,1]
	v_pk_add_f32 v[46:47], v[46:47], v[94:95] op_sel_hi:[1,0] neg_lo:[0,1] neg_hi:[0,1]
	v_pk_add_f32 v[64:65], v[64:65], v[94:95] op_sel_hi:[1,0] neg_lo:[0,1] neg_hi:[0,1]
	v_pk_add_f32 v[48:49], v[48:49], v[94:95] op_sel_hi:[1,0] neg_lo:[0,1] neg_hi:[0,1]
	v_pk_mul_f32 v[14:15], v[14:15], v[102:103] op_sel_hi:[1,0]
	v_pk_mul_f32 v[12:13], v[12:13], v[102:103] op_sel_hi:[1,0]
	v_pk_mul_f32 v[10:11], v[10:11], v[102:103] op_sel_hi:[1,0]
	v_pk_mul_f32 v[8:9], v[8:9], v[102:103] op_sel_hi:[1,0]
	v_pk_mul_f32 v[6:7], v[6:7], v[102:103] op_sel_hi:[1,0]
	v_pk_mul_f32 v[4:5], v[4:5], v[102:103] op_sel_hi:[1,0]
	v_pk_mul_f32 v[2:3], v[2:3], v[102:103] op_sel_hi:[1,0]
	v_pk_mul_f32 v[0:1], v[0:1], v[102:103] op_sel_hi:[1,0]
	v_pk_mul_f32 v[30:31], v[30:31], v[102:103] op_sel_hi:[1,0]
	v_pk_mul_f32 v[28:29], v[28:29], v[102:103] op_sel_hi:[1,0]
	v_pk_mul_f32 v[26:27], v[26:27], v[102:103] op_sel_hi:[1,0]
	v_pk_mul_f32 v[24:25], v[24:25], v[102:103] op_sel_hi:[1,0]
	v_pk_mul_f32 v[22:23], v[22:23], v[102:103] op_sel_hi:[1,0]
	v_pk_mul_f32 v[20:21], v[20:21], v[102:103] op_sel_hi:[1,0]
	v_pk_mul_f32 v[18:19], v[18:19], v[102:103] op_sel_hi:[1,0]
	v_pk_mul_f32 v[16:17], v[16:17], v[102:103] op_sel_hi:[1,0]
